# e9 plus shared-KV norm pass: gamma/scale/shift kept in registers and reloaded only when the batch index changes, forget-gate bias hoisted out of the row loop, per-row full vmcnt drain removed (stores
# speedup vs baseline: 1.0095x; 1.0095x over previous
.LBB0_691:
	s_or_b64 exec, exec, s[0:1]
	s_cmpk_gt_i32 s96, 0x7fff
	s_waitcnt vmcnt(0) lgkmcnt(0)
	s_barrier
	v_mbcnt_lo_u32_b32 v0, -1, 0
	v_mbcnt_hi_u32_b32 v0, -1, v0
	s_cbranch_scc1 .LBB0_699
	s_ashr_i32 s97, s96, 31
	s_lshl_b64 s[0:1], s[96:97], 11
	v_and_b32_e32 v2, 63, v0
	s_add_u32 s2, s44, s0
	s_addc_u32 s3, s45, s1
	v_lshlrev_b32_e32 v0, 3, v2
	global_load_dwordx2 v[32:33], v0, s[2:3]
	global_load_dwordx2 v[30:31], v0, s[2:3] offset:512
	global_load_dwordx2 v[26:27], v0, s[2:3] offset:1024
	global_load_dwordx2 v[28:29], v0, s[2:3] offset:1536
	s_load_dwordx2 s[2:3], s[88:89], 0x70
	s_load_dwordx2 s[40:41], s[88:89], 0x88
	s_load_dwordx2 s[52:53], s[88:89], 0x20
	v_mov_b32_e32 v13, v1
	v_lshlrev_b32_e32 v12, 4, v2
	s_mov_b64 s[74:75], s[22:23]
	v_cmp_gt_u32_e64 s[4:5], 16, v2
	s_waitcnt lgkmcnt(0)
	v_lshl_add_u64 v[6:7], s[52:53], 0, v[12:13]
	s_mov_b64 s[52:53], 0x3000
	v_lshlrev_b32_e32 v16, 2, v2
	v_cmp_eq_u32_e64 s[6:7], 15, v2
	v_cmp_eq_u32_e64 s[8:9], 14, v2
	v_cmp_eq_u32_e64 s[10:11], 13, v2
	v_cmp_eq_u32_e64 s[12:13], 12, v2
	v_cmp_eq_u32_e64 s[14:15], 11, v2
	v_cmp_eq_u32_e64 s[16:17], 10, v2
	v_cmp_eq_u32_e64 s[18:19], 9, v2
	v_cmp_eq_u32_e64 s[20:21], 8, v2
	v_cmp_eq_u32_e64 s[22:23], 7, v2
	v_cmp_eq_u32_e64 s[24:25], 6, v2
	v_cmp_eq_u32_e64 s[26:27], 5, v2
	v_cmp_eq_u32_e64 s[28:29], 4, v2
	v_cmp_eq_u32_e64 s[30:31], 3, v2
	v_cmp_eq_u32_e64 s[34:35], 2, v2
	v_cmp_eq_u32_e64 s[36:37], 1, v2
	v_cmp_eq_u32_e64 s[38:39], 0, v2
	v_lshl_add_u64 v[2:3], s[72:73], 0, v[12:13]
	v_lshl_add_u64 v[6:7], v[6:7], 0, s[52:53]
	s_mov_b64 s[52:53], 0x1000
	v_lshl_add_u64 v[10:11], s[46:47], 0, v[12:13]
	v_lshl_add_u64 v[8:9], v[2:3], 0, s[52:53]
	s_mov_b64 s[52:53], 0x149000
	v_lshl_add_u64 v[10:11], v[10:11], 0, s[52:53]
	s_lshl_b64 s[52:53], s[96:97], 6
	v_readlane_b32 s43, v255, 40
	v_lshl_add_u64 v[4:5], s[76:77], 0, v[12:13]
	v_add_u32_e32 v56, 0, v12
	s_add_u32 s52, s43, s52
	v_lshl_add_u64 v[12:13], s[2:3], 0, v[12:13]
	v_readlane_b32 s2, v255, 41
	v_mov_b32_e32 v17, v1
	s_addc_u32 s53, s2, s53
	s_ashr_i32 s55, s54, 31
	v_lshl_add_u64 v[14:15], s[40:41], 0, v[16:17]
	s_lshl_b64 s[40:41], s[54:55], 6
	v_lshl_add_u64 v[16:17], s[52:53], 0, v[16:17]
	s_add_u32 s52, s46, s0
	v_readlane_b32 s0, v255, 8
	s_addc_u32 s53, s47, s1
	s_add_i32 s0, s0, s54
	v_readlane_b32 s1, v255, 39
	s_add_i32 s0, s0, s1
	s_ashr_i32 s1, s0, 31
	s_lshl_b64 s[64:65], s[54:55], 11
	s_lshl_b64 s[0:1], s[0:1], 11
	s_add_u32 s44, s44, s0
	s_mov_b32 s50, s96
	s_addc_u32 s45, s45, s1
	s_waitcnt vmcnt(3)
	v_mov_b64_e32 v[18:19], v[32:33]
	s_waitcnt vmcnt(2)
	v_mov_b64_e32 v[20:21], v[30:31]
	s_waitcnt vmcnt(1)
	v_mov_b64_e32 v[22:23], v[26:27]
	s_waitcnt vmcnt(0)
	v_mov_b64_e32 v[24:25], v[28:29]
	s_mov_b32 s100, -1
	s_mov_b64 s[98:99], exec
	s_and_b64 exec, exec, s[4:5]
	global_load_dword v99, v[14:15], off
	s_mov_b64 exec, s[98:99]
	s_branch .LBB0_694
.LBB0_693:
	s_or_b64 exec, exec, s[0:1]
	s_waitcnt vmcnt(9)
	s_add_u32 s52, s52, s64
	s_addc_u32 s53, s53, s65
	s_add_u32 s44, s44, s64
	v_lshl_add_u64 v[16:17], v[16:17], 0, s[40:41]
	s_addc_u32 s45, s45, s65
	s_andn2_b64 vcc, exec, s[72:73]
	s_mov_b32 s50, s43
	v_mov_b64_e32 v[32:33], v[18:19]
	v_mov_b64_e32 v[30:31], v[20:21]
	v_mov_b64_e32 v[26:27], v[22:23]
	v_mov_b64_e32 v[28:29], v[24:25]
	s_cbranch_vccz .LBB0_698

.LBB0_696:
	s_ashr_i32 s2, s50, 13
	s_cmp_eq_u32 s2, s100
	s_cbranch_scc1 .Lmy_nk_noreload
	s_ashr_i32 s3, s2, 31
	v_mad_i64_i32 v[80:81], s[0:1], s2, v252, v[8:9]
	v_mad_i64_i32 v[82:83], s[0:1], s2, v252, v[2:3]
	s_lshl_b64 s[0:1], s[2:3], 13
	v_lshl_add_u64 v[84:85], v[4:5], 0, s[0:1]
	v_lshl_add_u64 v[86:87], v[10:11], 0, s[0:1]
	global_load_dwordx4 v[100:103], v[6:7], off
	global_load_dwordx4 v[104:107], v[80:81], off
	global_load_dwordx4 v[108:111], v[82:83], off
	global_load_dwordx4 v[112:115], v[6:7], off offset:1024
	global_load_dwordx4 v[116:119], v[80:81], off offset:1024
	global_load_dwordx4 v[120:123], v[82:83], off offset:1024
	global_load_dwordx4 v[124:127], v[6:7], off offset:2048
	global_load_dwordx4 v[128:131], v[80:81], off offset:2048
	global_load_dwordx4 v[132:135], v[82:83], off offset:2048
	global_load_dwordx4 v[136:139], v[6:7], off offset:3072
	global_load_dwordx4 v[140:143], v[80:81], off offset:3072
	global_load_dwordx4 v[144:147], v[82:83], off offset:3072
	global_load_dwordx4 v[148:151], v[12:13], off
	global_load_dwordx4 v[152:155], v[86:87], off
	global_load_dwordx4 v[156:159], v[84:85], off
	global_load_dwordx4 v[160:163], v[12:13], off offset:1024
	global_load_dwordx4 v[164:167], v[86:87], off offset:1024
	global_load_dwordx4 v[168:171], v[84:85], off offset:1024
	global_load_dwordx4 v[172:175], v[12:13], off offset:2048
	global_load_dwordx4 v[176:179], v[86:87], off offset:2048
	global_load_dwordx4 v[180:183], v[84:85], off offset:2048
	global_load_dwordx4 v[184:187], v[12:13], off offset:3072
	global_load_dwordx4 v[188:191], v[86:87], off offset:3072
	global_load_dwordx4 v[192:195], v[84:85], off offset:3072
	s_mov_b32 s100, s2
	s_waitcnt vmcnt(0)
.Lmy_nk_noreload:
	v_cvt_f32_f16_sdwa v43, v32 dst_sel:DWORD dst_unused:UNUSED_PAD src0_sel:WORD_1
	v_cvt_f32_f16_e32 v42, v32
	v_cvt_f32_f16_sdwa v41, v33 dst_sel:DWORD dst_unused:UNUSED_PAD src0_sel:WORD_1
	v_cvt_f32_f16_e32 v40, v33
	v_cvt_f32_f16_sdwa v45, v30 dst_sel:DWORD dst_unused:UNUSED_PAD src0_sel:WORD_1
	v_cvt_f32_f16_e32 v44, v30
	v_cvt_f32_f16_sdwa v47, v31 dst_sel:DWORD dst_unused:UNUSED_PAD src0_sel:WORD_1
	v_cvt_f32_f16_e32 v46, v31
	v_cvt_f32_f16_sdwa v37, v26 dst_sel:DWORD dst_unused:UNUSED_PAD src0_sel:WORD_1
	v_cvt_f32_f16_e32 v36, v26
	v_pk_mul_f32 v[32:33], v[42:43], v[42:43]
	v_pk_mul_f32 v[34:35], v[40:41], v[40:41]
	v_pk_mul_f32 v[48:49], v[44:45], v[44:45]
	v_pk_mul_f32 v[50:51], v[46:47], v[46:47]
	v_pk_mul_f32 v[52:53], v[36:37], v[36:37]
	v_add_f32_e32 v50, v50, v51
	v_add_f32_e32 v48, v48, v49
	v_add_f32_e32 v34, v34, v35
	v_add_f32_e32 v32, v32, v33
	v_add_f32_e32 v48, v48, v50
	v_add_f32_e32 v32, v32, v34
	v_add_f32_e32 v34, v52, v53
	v_cvt_f32_f16_sdwa v39, v27 dst_sel:DWORD dst_unused:UNUSED_PAD src0_sel:WORD_1
	v_cvt_f32_f16_e32 v38, v27
	v_cvt_f32_f16_sdwa v27, v28 dst_sel:DWORD dst_unused:UNUSED_PAD src0_sel:WORD_1
	v_cvt_f32_f16_e32 v26, v28
	v_cvt_f32_f16_sdwa v31, v29 dst_sel:DWORD dst_unused:UNUSED_PAD src0_sel:WORD_1
	v_cvt_f32_f16_e32 v30, v29
	v_pk_mul_f32 v[54:55], v[38:39], v[38:39]
	v_pk_mul_f32 v[28:29], v[26:27], v[26:27]
	v_add_f32_e32 v33, v54, v55
	v_pk_mul_f32 v[58:59], v[30:31], v[30:31]
	v_add_f32_e32 v32, v32, v48
	v_add_f32_e32 v33, v34, v33
	v_add_f32_e32 v32, v33, v32
	v_add_f32_e32 v33, v58, v59
	v_add_f32_e32 v28, v28, v29
	v_add_f32_e32 v28, v28, v33
	v_add_f32_e32 v28, v28, v32
	ds_swizzle_b32 v29, v28 offset:swizzle(SWAP,1)
	s_ashr_i32 s2, s50, 13
	v_mad_i64_i32 v[48:49], s[0:1], s2, v252, v[8:9]
	v_lshl_add_u64 v[34:35], s[52:53], 0, v[0:1]
	s_waitcnt lgkmcnt(0)
	v_add_f32_e32 v28, v28, v29
	ds_swizzle_b32 v29, v28 offset:swizzle(SWAP,2)
	s_ashr_i32 s3, s2, 31
	s_waitcnt lgkmcnt(0)
	v_add_f32_e32 v28, v28, v29
	ds_swizzle_b32 v29, v28 offset:swizzle(SWAP,4)
	s_waitcnt lgkmcnt(0)
	v_add_f32_e32 v28, v28, v29
	ds_swizzle_b32 v29, v28 offset:swizzle(SWAP,8)
	s_waitcnt lgkmcnt(0)
	v_add_f32_e32 v28, v28, v29
	ds_swizzle_b32 v29, v28 offset:swizzle(SWAP,16)
	s_waitcnt lgkmcnt(0)
	v_add_f32_e32 v28, v28, v29
	v_mov_b32_e32 v29, v28
	s_nop 1
	v_permlane32_swap_b32_e32 v28, v29
	v_add_f32_e32 v28, v28, v29
	v_fmamk_f32 v28, v28, 0x3a800000, v244
	v_rsq_f32_e32 v32, v28
	v_mad_i64_i32 v[28:29], s[0:1], s2, v252, v[2:3]
	s_mov_b32 s0, 0x1b400000
	v_pk_mul_f32 v[40:41], v[40:41], v[32:33] op_sel_hi:[1,0]
	v_pk_mul_f32 v[42:43], v[42:43], v[32:33] op_sel_hi:[1,0]
	v_pk_mul_f32 v[46:47], v[46:47], v[32:33] op_sel_hi:[1,0]
	v_pk_mul_f32 v[44:45], v[44:45], v[32:33] op_sel_hi:[1,0]
	v_pk_mul_f32 v[38:39], v[38:39], v[32:33] op_sel_hi:[1,0]
	v_pk_mul_f32 v[36:37], v[36:37], v[32:33] op_sel_hi:[1,0]
	v_mov_b64_e32 v[50:51], v[100:101]
	v_mov_b64_e32 v[52:53], v[102:103]
	v_pk_mul_f32 v[54:55], v[50:51], v[42:43]
	v_pk_mul_f32 v[58:59], v[52:53], v[40:41]
	v_mov_b64_e32 v[50:51], v[104:105]
	v_mov_b64_e32 v[52:53], v[106:107]
	v_pk_add_f32 v[60:61], v[52:53], 1.0 op_sel_hi:[1,0]
	v_pk_add_f32 v[62:63], v[50:51], 1.0 op_sel_hi:[1,0]
	v_mov_b64_e32 v[50:51], v[108:109]
	v_mov_b64_e32 v[52:53], v[110:111]
	v_pk_fma_f32 v[50:51], v[62:63], v[54:55], v[50:51]
	v_add_co_u32_e32 v54, vcc, s0, v34
	v_pk_fma_f32 v[52:53], v[60:61], v[58:59], v[52:53]
	s_nop 0
	v_addc_co_u32_e32 v55, vcc, 0, v35, vcc
	v_cvt_pk_bf16_f32 v50, v50, v51
	v_cvt_pk_bf16_f32 v51, v52, v53
	global_store_dwordx2 v[54:55], v[50:51], off
	v_mov_b64_e32 v[50:51], v[112:113]
	v_mov_b64_e32 v[52:53], v[114:115]
	s_lshl_b64 s[0:1], s[2:3], 13
	v_pk_mul_f32 v[58:59], v[50:51], v[44:45]
	v_pk_mul_f32 v[60:61], v[52:53], v[46:47]
	v_mov_b64_e32 v[50:51], v[116:117]
	v_mov_b64_e32 v[52:53], v[118:119]
	v_pk_add_f32 v[62:63], v[52:53], 1.0 op_sel_hi:[1,0]
	v_pk_add_f32 v[64:65], v[50:51], 1.0 op_sel_hi:[1,0]
	v_mov_b64_e32 v[50:51], v[120:121]
	v_mov_b64_e32 v[52:53], v[122:123]
	v_pk_fma_f32 v[50:51], v[64:65], v[58:59], v[50:51]
	v_pk_fma_f32 v[52:53], v[62:63], v[60:61], v[52:53]
	v_cvt_pk_bf16_f32 v50, v50, v51
	s_nop 0
	v_cvt_pk_bf16_f32 v51, v52, v53
	global_store_dwordx2 v[54:55], v[50:51], off offset:512
	v_mov_b64_e32 v[50:51], v[124:125]
	v_mov_b64_e32 v[52:53], v[126:127]
	v_pk_mul_f32 v[58:59], v[36:37], v[50:51]
	v_pk_mul_f32 v[60:61], v[38:39], v[52:53]
	v_mov_b64_e32 v[50:51], v[128:129]
	v_mov_b64_e32 v[52:53], v[130:131]
	v_pk_add_f32 v[62:63], v[52:53], 1.0 op_sel_hi:[1,0]
	v_pk_add_f32 v[64:65], v[50:51], 1.0 op_sel_hi:[1,0]
	v_mov_b64_e32 v[50:51], v[132:133]
	v_mov_b64_e32 v[52:53], v[134:135]
	v_pk_fma_f32 v[50:51], v[58:59], v[64:65], v[50:51]
	v_pk_fma_f32 v[52:53], v[60:61], v[62:63], v[52:53]
	v_cvt_pk_bf16_f32 v50, v50, v51
	s_nop 0
	v_cvt_pk_bf16_f32 v51, v52, v53
	global_store_dwordx2 v[54:55], v[50:51], off offset:1024
	v_pk_mul_f32 v[50:51], v[30:31], v[32:33] op_sel_hi:[1,0]
	v_pk_mul_f32 v[52:53], v[26:27], v[32:33] op_sel_hi:[1,0]
	v_mov_b64_e32 v[30:31], v[136:137]
	v_mov_b64_e32 v[32:33], v[138:139]
	v_pk_mul_f32 v[58:59], v[52:53], v[30:31]
	v_pk_mul_f32 v[60:61], v[50:51], v[32:33]
	v_mov_b64_e32 v[30:31], v[140:141]
	v_mov_b64_e32 v[32:33], v[142:143]
	s_nop 0
	v_mov_b64_e32 v[26:27], v[144:145]
	v_mov_b64_e32 v[28:29], v[146:147]
	v_lshl_add_u64 v[48:49], v[4:5], 0, s[0:1]
	v_pk_add_f32 v[30:31], v[30:31], 1.0 op_sel_hi:[1,0]
	v_pk_add_f32 v[32:33], v[32:33], 1.0 op_sel_hi:[1,0]
	v_pk_fma_f32 v[26:27], v[58:59], v[30:31], v[26:27]
	v_pk_fma_f32 v[28:29], v[60:61], v[32:33], v[28:29]
	v_cvt_pk_bf16_f32 v26, v26, v27
	s_nop 0
	v_cvt_pk_bf16_f32 v27, v28, v29
	global_store_dwordx2 v[54:55], v[26:27], off offset:1536
	v_mov_b64_e32 v[26:27], v[148:149]
	v_mov_b64_e32 v[28:29], v[150:151]
	v_lshl_add_u64 v[54:55], v[10:11], 0, s[0:1]
	s_mov_b32 s0, 0x3400000
	v_pk_mul_f32 v[32:33], v[42:43], v[26:27]
	v_pk_mul_f32 v[40:41], v[40:41], v[28:29]
	v_mov_b64_e32 v[26:27], v[152:153]
	v_mov_b64_e32 v[28:29], v[154:155]
	v_pk_add_f32 v[42:43], v[28:29], 1.0 op_sel_hi:[1,0]
	v_mov_b64_e32 v[28:29], v[156:157]
	v_mov_b64_e32 v[30:31], v[158:159]
	v_pk_add_f32 v[58:59], v[26:27], 1.0 op_sel_hi:[1,0]
	v_pk_fma_f32 v[26:27], v[40:41], v[42:43], v[30:31]
	v_pk_fma_f32 v[28:29], v[32:33], v[58:59], v[28:29]
	v_add_co_u32_e32 v58, vcc, s0, v34
	v_cvt_pk_bf16_f32 v30, v28, v29
	v_cvt_pk_bf16_f32 v31, v26, v27
	s_nop 1
	v_addc_co_u32_e32 v59, vcc, 0, v35, vcc
	global_store_dwordx2 v[58:59], v[30:31], off
	v_mov_b64_e32 v[30:31], v[160:161]
	v_mov_b64_e32 v[32:33], v[162:163]
	v_pk_mul_f32 v[40:41], v[44:45], v[30:31]
	v_pk_mul_f32 v[42:43], v[46:47], v[32:33]
	v_mov_b64_e32 v[30:31], v[164:165]
	v_mov_b64_e32 v[32:33], v[166:167]
	v_pk_add_f32 v[44:45], v[32:33], 1.0 op_sel_hi:[1,0]
	v_mov_b64_e32 v[32:33], v[168:169]
	v_mov_b64_e32 v[34:35], v[170:171]
	v_pk_add_f32 v[46:47], v[30:31], 1.0 op_sel_hi:[1,0]
	v_pk_fma_f32 v[30:31], v[42:43], v[44:45], v[34:35]
	v_pk_fma_f32 v[32:33], v[40:41], v[46:47], v[32:33]
	s_nop 0
	v_cvt_pk_bf16_f32 v34, v32, v33
	v_cvt_pk_bf16_f32 v35, v30, v31
	global_store_dwordx2 v[58:59], v[34:35], off offset:512
	v_mov_b64_e32 v[40:41], v[172:173]
	v_mov_b64_e32 v[42:43], v[174:175]
	v_pk_mul_f32 v[40:41], v[36:37], v[40:41]
	v_mov_b64_e32 v[34:35], v[176:177]
	v_mov_b64_e32 v[36:37], v[178:179]
	v_pk_mul_f32 v[38:39], v[38:39], v[42:43]
	v_pk_add_f32 v[42:43], v[36:37], 1.0 op_sel_hi:[1,0]
	v_pk_add_f32 v[44:45], v[34:35], 1.0 op_sel_hi:[1,0]
	v_mov_b64_e32 v[34:35], v[180:181]
	v_mov_b64_e32 v[36:37], v[182:183]
	v_pk_fma_f32 v[38:39], v[38:39], v[42:43], v[36:37]
	v_pk_fma_f32 v[40:41], v[40:41], v[44:45], v[34:35]
	s_nop 0
	v_cvt_pk_bf16_f32 v34, v40, v41
	v_cvt_pk_bf16_f32 v35, v38, v39
	global_store_dwordx2 v[58:59], v[34:35], off offset:1024
	v_mov_b64_e32 v[34:35], v[184:185]
	v_mov_b64_e32 v[36:37], v[186:187]
	v_pk_mul_f32 v[46:47], v[52:53], v[34:35]
	v_pk_mul_f32 v[50:51], v[50:51], v[36:37]
	v_mov_b64_e32 v[34:35], v[188:189]
	v_mov_b64_e32 v[36:37], v[190:191]
	v_mov_b64_e32 v[42:43], v[192:193]
	v_mov_b64_e32 v[44:45], v[194:195]
	v_pk_add_f32 v[36:37], v[36:37], 1.0 op_sel_hi:[1,0]
	v_pk_add_f32 v[52:53], v[34:35], 1.0 op_sel_hi:[1,0]
	v_pk_fma_f32 v[34:35], v[50:51], v[36:37], v[44:45]
	v_pk_fma_f32 v[36:37], v[46:47], v[52:53], v[42:43]
	s_nop 0
	v_cvt_pk_bf16_f32 v42, v36, v37
	v_cvt_pk_bf16_f32 v43, v34, v35
	global_store_dwordx2 v[58:59], v[42:43], off offset:1536
	v_mbcnt_lo_u32_b32 v96, -1, 0
	v_mbcnt_hi_u32_b32 v96, -1, v96
	ds_read_b128 v[196:199], v56
	ds_read_b128 v[200:203], v56 offset:1024
	ds_read_b128 v[204:207], v56 offset:2048
	ds_read_b128 v[208:211], v56 offset:3072
	ds_read_b128 v[212:215], v56 offset:4096
	ds_read_b128 v[216:219], v56 offset:5120
	ds_read_b128 v[220:223], v56 offset:6144
	ds_read_b128 v[224:227], v56 offset:7168
	v_lshrrev_b32_e32 v97, 2, v96
	v_and_b32_e32 v98, 3, v96
	v_lshl_or_b32 v97, v97, 4, v98
	v_and_b32_e32 v97, 63, v97
	v_lshlrev_b32_e32 v97, 2, v97
	s_waitcnt lgkmcnt(4)
	v_mul_f32_e32 v228, v29, v197
	v_mul_f32_e32 v229, v27, v199
	v_mul_f32_e32 v230, v33, v201
	v_mul_f32_e32 v231, v31, v203
	v_mul_f32_e32 v232, v41, v205
	v_mul_f32_e32 v233, v39, v207
	v_mul_f32_e32 v234, v37, v209
	v_mul_f32_e32 v235, v35, v211
	v_fmac_f32_e32 v228, v28, v196
	v_fmac_f32_e32 v229, v26, v198
	v_fmac_f32_e32 v230, v32, v200
	v_fmac_f32_e32 v231, v30, v202
	v_fmac_f32_e32 v232, v40, v204
	v_fmac_f32_e32 v233, v38, v206
	v_fmac_f32_e32 v234, v36, v208
	v_fmac_f32_e32 v235, v34, v210
	v_add_f32_e32 v228, v228, v229
	v_add_f32_e32 v230, v230, v231
	v_add_f32_e32 v232, v232, v233
	v_add_f32_e32 v234, v234, v235
	v_add_f32_e32 v80, 0, v228
	v_add_f32_e32 v80, v80, v230
	v_add_f32_e32 v80, v80, v232
	v_add_f32_e32 v80, v80, v234
	ds_read_b128 v[196:199], v56 offset:8192
	ds_read_b128 v[200:203], v56 offset:9216
	ds_read_b128 v[204:207], v56 offset:10240
	ds_read_b128 v[208:211], v56 offset:11264
	s_waitcnt lgkmcnt(4)
	v_mul_f32_e32 v228, v29, v213
	v_mul_f32_e32 v229, v27, v215
	v_mul_f32_e32 v230, v33, v217
	v_mul_f32_e32 v231, v31, v219
	v_mul_f32_e32 v232, v41, v221
	v_mul_f32_e32 v233, v39, v223
	v_mul_f32_e32 v234, v37, v225
	v_mul_f32_e32 v235, v35, v227
	v_fmac_f32_e32 v228, v28, v212
	v_fmac_f32_e32 v229, v26, v214
	v_fmac_f32_e32 v230, v32, v216
	v_fmac_f32_e32 v231, v30, v218
	v_fmac_f32_e32 v232, v40, v220
	v_fmac_f32_e32 v233, v38, v222
	v_fmac_f32_e32 v234, v36, v224
	v_fmac_f32_e32 v235, v34, v226
	v_add_f32_e32 v228, v228, v229
	v_add_f32_e32 v230, v230, v231
	v_add_f32_e32 v232, v232, v233
	v_add_f32_e32 v234, v234, v235
	v_add_f32_e32 v81, 0, v228
	v_add_f32_e32 v81, v81, v230
	v_add_f32_e32 v81, v81, v232
	v_add_f32_e32 v81, v81, v234
	ds_read_b128 v[212:215], v56 offset:12288
	ds_read_b128 v[216:219], v56 offset:13312
	ds_read_b128 v[220:223], v56 offset:14336
	ds_read_b128 v[224:227], v56 offset:15360
	s_waitcnt lgkmcnt(4)
	v_mul_f32_e32 v228, v29, v197
	v_mul_f32_e32 v229, v27, v199
	v_mul_f32_e32 v230, v33, v201
	v_mul_f32_e32 v231, v31, v203
	v_mul_f32_e32 v232, v41, v205
	v_mul_f32_e32 v233, v39, v207
	v_mul_f32_e32 v234, v37, v209
	v_mul_f32_e32 v235, v35, v211
	v_fmac_f32_e32 v228, v28, v196
	v_fmac_f32_e32 v229, v26, v198
	v_fmac_f32_e32 v230, v32, v200
	v_fmac_f32_e32 v231, v30, v202
	v_fmac_f32_e32 v232, v40, v204
	v_fmac_f32_e32 v233, v38, v206
	v_fmac_f32_e32 v234, v36, v208
	v_fmac_f32_e32 v235, v34, v210
	v_add_f32_e32 v228, v228, v229
	v_add_f32_e32 v230, v230, v231
	v_add_f32_e32 v232, v232, v233
	v_add_f32_e32 v234, v234, v235
	v_add_f32_e32 v82, 0, v228
	v_add_f32_e32 v82, v82, v230
	v_add_f32_e32 v82, v82, v232
	v_add_f32_e32 v82, v82, v234
	ds_read_b128 v[196:199], v56 offset:16384
	ds_read_b128 v[200:203], v56 offset:17408
	ds_read_b128 v[204:207], v56 offset:18432
	ds_read_b128 v[208:211], v56 offset:19456
	s_waitcnt lgkmcnt(4)
	v_mul_f32_e32 v228, v29, v213
	v_mul_f32_e32 v229, v27, v215
	v_mul_f32_e32 v230, v33, v217
	v_mul_f32_e32 v231, v31, v219
	v_mul_f32_e32 v232, v41, v221
	v_mul_f32_e32 v233, v39, v223
	v_mul_f32_e32 v234, v37, v225
	v_mul_f32_e32 v235, v35, v227
	v_fmac_f32_e32 v228, v28, v212
	v_fmac_f32_e32 v229, v26, v214
	v_fmac_f32_e32 v230, v32, v216
	v_fmac_f32_e32 v231, v30, v218
	v_fmac_f32_e32 v232, v40, v220
	v_fmac_f32_e32 v233, v38, v222
	v_fmac_f32_e32 v234, v36, v224
	v_fmac_f32_e32 v235, v34, v226
	v_add_f32_e32 v228, v228, v229
	v_add_f32_e32 v230, v230, v231
	v_add_f32_e32 v232, v232, v233
	v_add_f32_e32 v234, v234, v235
	v_add_f32_e32 v83, 0, v228
	v_add_f32_e32 v83, v83, v230
	v_add_f32_e32 v83, v83, v232
	v_add_f32_e32 v83, v83, v234
	ds_read_b128 v[212:215], v56 offset:20480
	ds_read_b128 v[216:219], v56 offset:21504
	ds_read_b128 v[220:223], v56 offset:22528
	ds_read_b128 v[224:227], v56 offset:23552
	s_waitcnt lgkmcnt(4)
	v_mul_f32_e32 v228, v29, v197
	v_mul_f32_e32 v229, v27, v199
	v_mul_f32_e32 v230, v33, v201
	v_mul_f32_e32 v231, v31, v203
	v_mul_f32_e32 v232, v41, v205
	v_mul_f32_e32 v233, v39, v207
	v_mul_f32_e32 v234, v37, v209
	v_mul_f32_e32 v235, v35, v211
	v_fmac_f32_e32 v228, v28, v196
	v_fmac_f32_e32 v229, v26, v198
	v_fmac_f32_e32 v230, v32, v200
	v_fmac_f32_e32 v231, v30, v202
	v_fmac_f32_e32 v232, v40, v204
	v_fmac_f32_e32 v233, v38, v206
	v_fmac_f32_e32 v234, v36, v208
	v_fmac_f32_e32 v235, v34, v210
	v_add_f32_e32 v228, v228, v229
	v_add_f32_e32 v230, v230, v231
	v_add_f32_e32 v232, v232, v233
	v_add_f32_e32 v234, v234, v235
	v_add_f32_e32 v84, 0, v228
	v_add_f32_e32 v84, v84, v230
	v_add_f32_e32 v84, v84, v232
	v_add_f32_e32 v84, v84, v234
	ds_read_b128 v[196:199], v56 offset:24576
	ds_read_b128 v[200:203], v56 offset:25600
	ds_read_b128 v[204:207], v56 offset:26624
	ds_read_b128 v[208:211], v56 offset:27648
	s_waitcnt lgkmcnt(4)
	v_mul_f32_e32 v228, v29, v213
	v_mul_f32_e32 v229, v27, v215
	v_mul_f32_e32 v230, v33, v217
	v_mul_f32_e32 v231, v31, v219
	v_mul_f32_e32 v232, v41, v221
	v_mul_f32_e32 v233, v39, v223
	v_mul_f32_e32 v234, v37, v225
	v_mul_f32_e32 v235, v35, v227
	v_fmac_f32_e32 v228, v28, v212
	v_fmac_f32_e32 v229, v26, v214
	v_fmac_f32_e32 v230, v32, v216
	v_fmac_f32_e32 v231, v30, v218
	v_fmac_f32_e32 v232, v40, v220
	v_fmac_f32_e32 v233, v38, v222
	v_fmac_f32_e32 v234, v36, v224
	v_fmac_f32_e32 v235, v34, v226
	v_add_f32_e32 v228, v228, v229
	v_add_f32_e32 v230, v230, v231
	v_add_f32_e32 v232, v232, v233
	v_add_f32_e32 v234, v234, v235
	v_add_f32_e32 v85, 0, v228
	v_add_f32_e32 v85, v85, v230
	v_add_f32_e32 v85, v85, v232
	v_add_f32_e32 v85, v85, v234
	ds_read_b128 v[212:215], v56 offset:28672
	ds_read_b128 v[216:219], v56 offset:29696
	ds_read_b128 v[220:223], v56 offset:30720
	ds_read_b128 v[224:227], v56 offset:31744
	s_waitcnt lgkmcnt(4)
	v_mul_f32_e32 v228, v29, v197
	v_mul_f32_e32 v229, v27, v199
	v_mul_f32_e32 v230, v33, v201
	v_mul_f32_e32 v231, v31, v203
	v_mul_f32_e32 v232, v41, v205
	v_mul_f32_e32 v233, v39, v207
	v_mul_f32_e32 v234, v37, v209
	v_mul_f32_e32 v235, v35, v211
	v_fmac_f32_e32 v228, v28, v196
	v_fmac_f32_e32 v229, v26, v198
	v_fmac_f32_e32 v230, v32, v200
	v_fmac_f32_e32 v231, v30, v202
	v_fmac_f32_e32 v232, v40, v204
	v_fmac_f32_e32 v233, v38, v206
	v_fmac_f32_e32 v234, v36, v208
	v_fmac_f32_e32 v235, v34, v210
	v_add_f32_e32 v228, v228, v229
	v_add_f32_e32 v230, v230, v231
	v_add_f32_e32 v232, v232, v233
	v_add_f32_e32 v234, v234, v235
	v_add_f32_e32 v86, 0, v228
	v_add_f32_e32 v86, v86, v230
	v_add_f32_e32 v86, v86, v232
	v_add_f32_e32 v86, v86, v234
	ds_read_b128 v[196:199], v56 offset:32768
	ds_read_b128 v[200:203], v56 offset:33792
	ds_read_b128 v[204:207], v56 offset:34816
	ds_read_b128 v[208:211], v56 offset:35840
	s_waitcnt lgkmcnt(4)
	v_mul_f32_e32 v228, v29, v213
	v_mul_f32_e32 v229, v27, v215
	v_mul_f32_e32 v230, v33, v217
	v_mul_f32_e32 v231, v31, v219
	v_mul_f32_e32 v232, v41, v221
	v_mul_f32_e32 v233, v39, v223
	v_mul_f32_e32 v234, v37, v225
	v_mul_f32_e32 v235, v35, v227
	v_fmac_f32_e32 v228, v28, v212
	v_fmac_f32_e32 v229, v26, v214
	v_fmac_f32_e32 v230, v32, v216
	v_fmac_f32_e32 v231, v30, v218
	v_fmac_f32_e32 v232, v40, v220
	v_fmac_f32_e32 v233, v38, v222
	v_fmac_f32_e32 v234, v36, v224
	v_fmac_f32_e32 v235, v34, v226
	v_add_f32_e32 v228, v228, v229
	v_add_f32_e32 v230, v230, v231
	v_add_f32_e32 v232, v232, v233
	v_add_f32_e32 v234, v234, v235
	v_add_f32_e32 v87, 0, v228
	v_add_f32_e32 v87, v87, v230
	v_add_f32_e32 v87, v87, v232
	v_add_f32_e32 v87, v87, v234
	ds_read_b128 v[212:215], v56 offset:36864
	ds_read_b128 v[216:219], v56 offset:37888
	ds_read_b128 v[220:223], v56 offset:38912
	ds_read_b128 v[224:227], v56 offset:39936
	s_waitcnt lgkmcnt(4)
	v_mul_f32_e32 v228, v29, v197
	v_mul_f32_e32 v229, v27, v199
	v_mul_f32_e32 v230, v33, v201
	v_mul_f32_e32 v231, v31, v203
	v_mul_f32_e32 v232, v41, v205
	v_mul_f32_e32 v233, v39, v207
	v_mul_f32_e32 v234, v37, v209
	v_mul_f32_e32 v235, v35, v211
	v_fmac_f32_e32 v228, v28, v196
	v_fmac_f32_e32 v229, v26, v198
	v_fmac_f32_e32 v230, v32, v200
	v_fmac_f32_e32 v231, v30, v202
	v_fmac_f32_e32 v232, v40, v204
	v_fmac_f32_e32 v233, v38, v206
	v_fmac_f32_e32 v234, v36, v208
	v_fmac_f32_e32 v235, v34, v210
	v_add_f32_e32 v228, v228, v229
	v_add_f32_e32 v230, v230, v231
	v_add_f32_e32 v232, v232, v233
	v_add_f32_e32 v234, v234, v235
	v_add_f32_e32 v88, 0, v228
	v_add_f32_e32 v88, v88, v230
	v_add_f32_e32 v88, v88, v232
	v_add_f32_e32 v88, v88, v234
	ds_read_b128 v[196:199], v56 offset:40960
	ds_read_b128 v[200:203], v56 offset:41984
	ds_read_b128 v[204:207], v56 offset:43008
	ds_read_b128 v[208:211], v56 offset:44032
	s_waitcnt lgkmcnt(4)
	v_mul_f32_e32 v228, v29, v213
	v_mul_f32_e32 v229, v27, v215
	v_mul_f32_e32 v230, v33, v217
	v_mul_f32_e32 v231, v31, v219
	v_mul_f32_e32 v232, v41, v221
	v_mul_f32_e32 v233, v39, v223
	v_mul_f32_e32 v234, v37, v225
	v_mul_f32_e32 v235, v35, v227
	v_fmac_f32_e32 v228, v28, v212
	v_fmac_f32_e32 v229, v26, v214
	v_fmac_f32_e32 v230, v32, v216
	v_fmac_f32_e32 v231, v30, v218
	v_fmac_f32_e32 v232, v40, v220
	v_fmac_f32_e32 v233, v38, v222
	v_fmac_f32_e32 v234, v36, v224
	v_fmac_f32_e32 v235, v34, v226
	v_add_f32_e32 v228, v228, v229
	v_add_f32_e32 v230, v230, v231
	v_add_f32_e32 v232, v232, v233
	v_add_f32_e32 v234, v234, v235
	v_add_f32_e32 v89, 0, v228
	v_add_f32_e32 v89, v89, v230
	v_add_f32_e32 v89, v89, v232
	v_add_f32_e32 v89, v89, v234
	ds_read_b128 v[212:215], v56 offset:45056
	ds_read_b128 v[216:219], v56 offset:46080
	ds_read_b128 v[220:223], v56 offset:47104
	ds_read_b128 v[224:227], v56 offset:48128
	s_waitcnt lgkmcnt(4)
	v_mul_f32_e32 v228, v29, v197
	v_mul_f32_e32 v229, v27, v199
	v_mul_f32_e32 v230, v33, v201
	v_mul_f32_e32 v231, v31, v203
	v_mul_f32_e32 v232, v41, v205
	v_mul_f32_e32 v233, v39, v207
	v_mul_f32_e32 v234, v37, v209
	v_mul_f32_e32 v235, v35, v211
	v_fmac_f32_e32 v228, v28, v196
	v_fmac_f32_e32 v229, v26, v198
	v_fmac_f32_e32 v230, v32, v200
	v_fmac_f32_e32 v231, v30, v202
	v_fmac_f32_e32 v232, v40, v204
	v_fmac_f32_e32 v233, v38, v206
	v_fmac_f32_e32 v234, v36, v208
	v_fmac_f32_e32 v235, v34, v210
	v_add_f32_e32 v228, v228, v229
	v_add_f32_e32 v230, v230, v231
	v_add_f32_e32 v232, v232, v233
	v_add_f32_e32 v234, v234, v235
	v_add_f32_e32 v90, 0, v228
	v_add_f32_e32 v90, v90, v230
	v_add_f32_e32 v90, v90, v232
	v_add_f32_e32 v90, v90, v234
	ds_read_b128 v[196:199], v56 offset:49152
	ds_read_b128 v[200:203], v56 offset:50176
	ds_read_b128 v[204:207], v56 offset:51200
	ds_read_b128 v[208:211], v56 offset:52224
	s_waitcnt lgkmcnt(4)
	v_mul_f32_e32 v228, v29, v213
	v_mul_f32_e32 v229, v27, v215
	v_mul_f32_e32 v230, v33, v217
	v_mul_f32_e32 v231, v31, v219
	v_mul_f32_e32 v232, v41, v221
	v_mul_f32_e32 v233, v39, v223
	v_mul_f32_e32 v234, v37, v225
	v_mul_f32_e32 v235, v35, v227
	v_fmac_f32_e32 v228, v28, v212
	v_fmac_f32_e32 v229, v26, v214
	v_fmac_f32_e32 v230, v32, v216
	v_fmac_f32_e32 v231, v30, v218
	v_fmac_f32_e32 v232, v40, v220
	v_fmac_f32_e32 v233, v38, v222
	v_fmac_f32_e32 v234, v36, v224
	v_fmac_f32_e32 v235, v34, v226
	v_add_f32_e32 v228, v228, v229
	v_add_f32_e32 v230, v230, v231
	v_add_f32_e32 v232, v232, v233
	v_add_f32_e32 v234, v234, v235
	v_add_f32_e32 v91, 0, v228
	v_add_f32_e32 v91, v91, v230
	v_add_f32_e32 v91, v91, v232
	v_add_f32_e32 v91, v91, v234
	ds_read_b128 v[212:215], v56 offset:53248
	ds_read_b128 v[216:219], v56 offset:54272
	ds_read_b128 v[220:223], v56 offset:55296
	ds_read_b128 v[224:227], v56 offset:56320
	s_waitcnt lgkmcnt(4)
	v_mul_f32_e32 v228, v29, v197
	v_mul_f32_e32 v229, v27, v199
	v_mul_f32_e32 v230, v33, v201
	v_mul_f32_e32 v231, v31, v203
	v_mul_f32_e32 v232, v41, v205
	v_mul_f32_e32 v233, v39, v207
	v_mul_f32_e32 v234, v37, v209
	v_mul_f32_e32 v235, v35, v211
	v_fmac_f32_e32 v228, v28, v196
	v_fmac_f32_e32 v229, v26, v198
	v_fmac_f32_e32 v230, v32, v200
	v_fmac_f32_e32 v231, v30, v202
	v_fmac_f32_e32 v232, v40, v204
	v_fmac_f32_e32 v233, v38, v206
	v_fmac_f32_e32 v234, v36, v208
	v_fmac_f32_e32 v235, v34, v210
	v_add_f32_e32 v228, v228, v229
	v_add_f32_e32 v230, v230, v231
	v_add_f32_e32 v232, v232, v233
	v_add_f32_e32 v234, v234, v235
	v_add_f32_e32 v92, 0, v228
	v_add_f32_e32 v92, v92, v230
	v_add_f32_e32 v92, v92, v232
	v_add_f32_e32 v92, v92, v234
	ds_read_b128 v[196:199], v56 offset:57344
	ds_read_b128 v[200:203], v56 offset:58368
	ds_read_b128 v[204:207], v56 offset:59392
	ds_read_b128 v[208:211], v56 offset:60416
	s_waitcnt lgkmcnt(4)
	v_mul_f32_e32 v228, v29, v213
	v_mul_f32_e32 v229, v27, v215
	v_mul_f32_e32 v230, v33, v217
	v_mul_f32_e32 v231, v31, v219
	v_mul_f32_e32 v232, v41, v221
	v_mul_f32_e32 v233, v39, v223
	v_mul_f32_e32 v234, v37, v225
	v_mul_f32_e32 v235, v35, v227
	v_fmac_f32_e32 v228, v28, v212
	v_fmac_f32_e32 v229, v26, v214
	v_fmac_f32_e32 v230, v32, v216
	v_fmac_f32_e32 v231, v30, v218
	v_fmac_f32_e32 v232, v40, v220
	v_fmac_f32_e32 v233, v38, v222
	v_fmac_f32_e32 v234, v36, v224
	v_fmac_f32_e32 v235, v34, v226
	v_add_f32_e32 v228, v228, v229
	v_add_f32_e32 v230, v230, v231
	v_add_f32_e32 v232, v232, v233
	v_add_f32_e32 v234, v234, v235
	v_add_f32_e32 v93, 0, v228
	v_add_f32_e32 v93, v93, v230
	v_add_f32_e32 v93, v93, v232
	v_add_f32_e32 v93, v93, v234
	ds_read_b128 v[212:215], v56 offset:61440
	ds_read_b128 v[216:219], v56 offset:62464
	ds_read_b128 v[220:223], v56 offset:63488
	ds_read_b128 v[224:227], v56 offset:64512
	s_waitcnt lgkmcnt(4)
	v_mul_f32_e32 v228, v29, v197
	v_mul_f32_e32 v229, v27, v199
	v_mul_f32_e32 v230, v33, v201
	v_mul_f32_e32 v231, v31, v203
	v_mul_f32_e32 v232, v41, v205
	v_mul_f32_e32 v233, v39, v207
	v_mul_f32_e32 v234, v37, v209
	v_mul_f32_e32 v235, v35, v211
	v_fmac_f32_e32 v228, v28, v196
	v_fmac_f32_e32 v229, v26, v198
	v_fmac_f32_e32 v230, v32, v200
	v_fmac_f32_e32 v231, v30, v202
	v_fmac_f32_e32 v232, v40, v204
	v_fmac_f32_e32 v233, v38, v206
	v_fmac_f32_e32 v234, v36, v208
	v_fmac_f32_e32 v235, v34, v210
	v_add_f32_e32 v228, v228, v229
	v_add_f32_e32 v230, v230, v231
	v_add_f32_e32 v232, v232, v233
	v_add_f32_e32 v234, v234, v235
	v_add_f32_e32 v94, 0, v228
	v_add_f32_e32 v94, v94, v230
	v_add_f32_e32 v94, v94, v232
	v_add_f32_e32 v94, v94, v234
	s_waitcnt lgkmcnt(0)
	v_mul_f32_e32 v228, v29, v213
	v_mul_f32_e32 v229, v27, v215
	v_mul_f32_e32 v230, v33, v217
	v_mul_f32_e32 v231, v31, v219
	v_mul_f32_e32 v232, v41, v221
	v_mul_f32_e32 v233, v39, v223
	v_mul_f32_e32 v234, v37, v225
	v_mul_f32_e32 v235, v35, v227
	v_fmac_f32_e32 v228, v28, v212
	v_fmac_f32_e32 v229, v26, v214
	v_fmac_f32_e32 v230, v32, v216
	v_fmac_f32_e32 v231, v30, v218
	v_fmac_f32_e32 v232, v40, v220
	v_fmac_f32_e32 v233, v38, v222
	v_fmac_f32_e32 v234, v36, v224
	v_fmac_f32_e32 v235, v34, v226
	v_add_f32_e32 v228, v228, v229
	v_add_f32_e32 v230, v230, v231
	v_add_f32_e32 v232, v232, v233
	v_add_f32_e32 v234, v234, v235
	v_add_f32_e32 v95, 0, v228
	v_add_f32_e32 v95, v95, v230
	v_add_f32_e32 v95, v95, v232
	v_add_f32_e32 v95, v95, v234
	v_permlane32_swap_b32_e32 v80, v88
	v_permlane32_swap_b32_e32 v81, v89
	v_permlane32_swap_b32_e32 v82, v90
	v_permlane32_swap_b32_e32 v83, v91
	v_permlane32_swap_b32_e32 v84, v92
	v_permlane32_swap_b32_e32 v85, v93
	v_permlane32_swap_b32_e32 v86, v94
	v_permlane32_swap_b32_e32 v87, v95
	v_add_f32_e32 v80, v80, v88
	v_add_f32_e32 v81, v81, v89
	v_add_f32_e32 v82, v82, v90
	v_add_f32_e32 v83, v83, v91
	v_add_f32_e32 v84, v84, v92
	v_add_f32_e32 v85, v85, v93
	v_add_f32_e32 v86, v86, v94
	v_add_f32_e32 v87, v87, v95
	s_mov_b32 vcc_lo, 0xffff0000
	s_mov_b32 vcc_hi, 0xffff0000
	v_cndmask_b32_e32 v240, v84, v80, vcc
	v_cndmask_b32_e32 v241, v85, v81, vcc
	v_cndmask_b32_e32 v242, v86, v82, vcc
	v_cndmask_b32_e32 v243, v87, v83, vcc
	v_cndmask_b32_e32 v236, v80, v84, vcc
	v_cndmask_b32_e32 v237, v81, v85, vcc
	v_cndmask_b32_e32 v238, v82, v86, vcc
	v_cndmask_b32_e32 v239, v83, v87, vcc
	ds_swizzle_b32 v232, v240 offset:swizzle(SWAP,16)
	ds_swizzle_b32 v233, v241 offset:swizzle(SWAP,16)
	ds_swizzle_b32 v234, v242 offset:swizzle(SWAP,16)
	ds_swizzle_b32 v235, v243 offset:swizzle(SWAP,16)
	s_waitcnt lgkmcnt(0)
	v_add_f32_e32 v88, v236, v232
	v_add_f32_e32 v89, v237, v233
	v_add_f32_e32 v90, v238, v234
	v_add_f32_e32 v91, v239, v235
	v_add_f32_dpp v88, v88, v88 row_ror:8 row_mask:0xf bank_mask:0xf
	v_add_f32_dpp v89, v89, v89 row_ror:8 row_mask:0xf bank_mask:0xf
	v_add_f32_dpp v90, v90, v90 row_ror:8 row_mask:0xf bank_mask:0xf
	v_add_f32_dpp v91, v91, v91 row_ror:8 row_mask:0xf bank_mask:0xf
	v_add_f32_dpp v88, v88, v88 row_ror:4 row_mask:0xf bank_mask:0xf
	v_add_f32_dpp v89, v89, v89 row_ror:4 row_mask:0xf bank_mask:0xf
	v_add_f32_dpp v90, v90, v90 row_ror:4 row_mask:0xf bank_mask:0xf
	v_add_f32_dpp v91, v91, v91 row_ror:4 row_mask:0xf bank_mask:0xf
	v_add_f32_dpp v88, v88, v88 quad_perm:[2,3,0,1] row_mask:0xf bank_mask:0xf
	v_add_f32_dpp v89, v89, v89 quad_perm:[2,3,0,1] row_mask:0xf bank_mask:0xf
	v_add_f32_dpp v90, v90, v90 quad_perm:[2,3,0,1] row_mask:0xf bank_mask:0xf
	v_add_f32_dpp v91, v91, v91 quad_perm:[2,3,0,1] row_mask:0xf bank_mask:0xf
	v_add_f32_dpp v88, v88, v88 quad_perm:[1,0,3,2] row_mask:0xf bank_mask:0xf
	v_add_f32_dpp v89, v89, v89 quad_perm:[1,0,3,2] row_mask:0xf bank_mask:0xf
	v_add_f32_dpp v90, v90, v90 quad_perm:[1,0,3,2] row_mask:0xf bank_mask:0xf
	v_add_f32_dpp v91, v91, v91 quad_perm:[1,0,3,2] row_mask:0xf bank_mask:0xf
	s_mov_b32 vcc_lo, 0xaaaaaaaa
	s_mov_b32 vcc_hi, 0xaaaaaaaa
	v_cndmask_b32_e32 v92, v88, v89, vcc
	v_cndmask_b32_e32 v93, v90, v91, vcc
	s_mov_b32 vcc_lo, 0xcccccccc
	s_mov_b32 vcc_hi, 0xcccccccc
	v_cndmask_b32_e32 v92, v92, v93, vcc
	ds_bpermute_b32 v26, v97, v92
	s_waitcnt lgkmcnt(0)
	s_and_saveexec_b64 s[0:1], s[4:5]
	s_cbranch_execz .LBB0_693
	s_mov_b32 s2, 0xbfb8aa3b
	v_add_f32_e32 v26, v26, v99
	v_mul_f32_e64 v27, |v26|, s2
	v_exp_f32_e32 v27, v27
	v_min_f32_e32 v26, 0, v26
	v_add_f32_e32 v27, 1.0, v27
	v_log_f32_e32 v27, v27
	s_nop 0
	v_fmac_f32_e32 v26, 0xbf317218, v27
	global_store_dword v[16:17], v26, off
	s_branch .LBB0_693
